# E10 + mixer C unit epilogue gate loads issued together up front; 8 bytes of unreachable padding keep the attention loop fetch phase
# baseline (speedup 1.0000x reference)
;   #define DMA_K(t, slot) glds16(ksrc + (long)(t) * KVBLK * PQ, (unsigned)__builtin_amdgcn_readfirstlane(kdst + (slot)))
; template <int THRL> __device__ __forceinline__ void attn_unit(const int tid, const float mfix, int q0, int NT, const bf16* Qh, const bf16* __restrict__ Kh, const bf16* __restrict__ Vh, const bf16* Zh, bf16* Oh, const long PQ, const long PO, char* shm) {
;   const int lane = tid & 63, r32 = lane & 31, hi = lane >> 5; const int wid = __builtin_amdgcn_readfirstlane(tid >> 6);
;   const bf16* Qw = Qh + (long)(q0 + wid * QBLK) * PQ;
;   const unsigned lds0 = (unsigned)(uintptr_t)shm;
;   float* wsf = (float*)(shm + LDS_WS) + wid * 64;
;   const bf16* ksrc = Kh + (long)lane * PQ + wid * 8;
;   const bf16* vsrc = Vh + (long)(16 * (wid & 3) + (lane >> 2)) * PQ + (wid >> 2) * 32 + (lane & 3) * 8;
;   const unsigned kdst = lds0 + LDS_K + wid * 1024, vdst = lds0 + LDS_V + wid * 1024;
;     ...
;   const int vb0 = (int)(lds0 + LDS_V) + ((lane >> 4) & 1) * 32 + (lane & 3) * 8 + (4 * hi + ((lane & 15) >> 2)) * 64;
;   const char* Kbase = shm + LDS_K; bf16x8 kf[8];
;   const lds_cptr shm3 = (lds_cptr)shm; const lds_cptr kp0 = shm3 + LDS_K + hi * 1024 + r32 * 16; const lds_cptr vp0 = shm3 + LDS_V + ((lane >> 4) & 1) * 32 + (lane & 3) * 8 + (4 * hi + ((lane & 15) >> 2)) * 64;
;   DMA_K(0, 0); DMA_V(0, 0); DMA_K(1, SLOTB);
;   bf16x8 qr[4];
;   #pragma unroll
;   for (int d0 = 0; d0 < 4; ++d0) qr[d0] = *reinterpret_cast<const bf16x8*>(&Qw[(long)r32 * PQ + d0 * 16 + hi * 8]);
;   float zf_; asm volatile("v_mov_b32 %0, 0" : "=v"(zf_)); f32x16 zv_;
;   #pragma unroll
;   for (int r = 0; r < 16; ++r) zv_[r] = zf_;
;   float l_reg = 0.f; f32x16 o[2]; o[0] = zv_; o[1] = zv_; f32x16 negm;
;   #pragma unroll
;   for (int r = 0; r < 16; ++r) negm[r] = -mfix;
;   asm volatile("" : "+v"(negm));
; __global__ void __launch_bounds__(NWAVES * 64, 2) mk_fwd(Args args) {
;     ...
;                 const int h = vcu >> 5;
;                 float mq = __builtin_fabsf(q_norm_w[l * 64 + lane]), mk = __builtin_fabsf(k_norm_w[l * 64 + lane]);
; #pragma unroll
;                 for (int o_ = 1; o_ < 64; o_ <<= 1) { mq = __builtin_fmaxf(mq, __shfl_xor(mq, o_)); mk = __builtin_fmaxf(mk, __shfl_xor(mk, o_)); }
;                 const float mfix = __int_as_float(__builtin_amdgcn_readfirstlane(__float_as_int(8.f * mq * mk * LOG2E * 1.02f)));
.LBB0_385:
	s_mov_b64 s[8:9], 0
	s_add_u32 s10, s62, s8
	s_addc_u32 s11, s63, s9
	s_load_dwordx4 s[4:7], s[10:11], 0x48
	v_and_b32_e32 v17, 63, v238
	v_lshl_or_b32 v188, s68, 6, v17
	v_lshlrev_b64 v[0:1], 2, v[188:189]
	v_xor_b32_e32 v4, 1, v252
	s_waitcnt lgkmcnt(0)
	v_lshl_add_u64 v[2:3], s[4:5], 0, v[0:1]
	v_lshl_add_u64 v[0:1], s[6:7], 0, v[0:1]
	global_load_dword v2, v[2:3], off
	s_nop 0
	global_load_dword v3, v[0:1], off
	v_and_b32_e32 v0, 64, v252
	v_add_u32_e32 v0, 64, v0
	v_lshlrev_b32_e32 v11, 4, v238
	v_cmp_lt_i32_e32 vcc, v4, v0
	v_bfe_u32 v18, v238, 5, 1
	v_and_b32_e32 v11, 0xc0, v11
	v_cndmask_b32_e32 v4, v252, v4, vcc
	v_mul_u32_u24_e32 v12, 0x1a40, v17
	v_lshl_or_b32 v20, v18, 8, v11
	v_lshlrev_b32_e32 v4, 2, v4
	v_lshlrev_b32_e32 v188, 1, v12
	v_xor_b32_e32 v5, 2, v252
	v_cmp_lt_i32_e32 vcc, v5, v0
	v_xor_b32_e32 v6, 4, v252
	s_add_u32 s14, s48, s8
	v_cndmask_b32_e32 v5, v252, v5, vcc
	v_lshlrev_b32_e32 v5, 2, v5
	v_cmp_lt_i32_e32 vcc, v6, v0
	s_addc_u32 s15, s49, s9
	s_lshl_b32 s4, s0, 1
	s_ashr_i32 s5, s0, 1
	v_cndmask_b32_e32 v6, v252, v6, vcc
	s_and_b32 s0, s4, 62
	s_andn2_b32 s4, s4, 63
	s_and_b32 s6, s5, 0xffffffc0
	v_lshlrev_b32_e32 v6, 2, v6
	s_ashr_i32 s5, s4, 31
	s_ashr_i32 s7, s6, 31
	s_lshl_b64 s[4:5], s[4:5], 1
	s_lshl_b64 s[10:11], s[6:7], 1
	s_add_u32 s12, s14, s10
	s_addc_u32 s13, s15, s11
	v_xor_b32_e32 v7, 8, v252
	s_add_u32 s6, s12, 0xd001f00
	v_cmp_lt_i32_e32 vcc, v7, v0
	s_addc_u32 s7, s13, 0
	v_xor_b32_e32 v8, 16, v252
	v_cndmask_b32_e32 v7, v252, v7, vcc
	v_lshlrev_b32_e32 v7, 2, v7
	v_cmp_lt_i32_e32 vcc, v8, v0
	v_and_b32_e32 v239, 31, v238
	v_xor_b32_e32 v9, 32, v252
	v_cndmask_b32_e32 v8, v252, v8, vcc
	v_lshlrev_b32_e32 v8, 2, v8
	v_mul_u32_u24_e32 v15, 0x1a40, v239
	v_lshlrev_b32_e32 v241, 4, v18
	v_mov_b32_e32 v1, v189
	v_cmp_lt_i32_e32 vcc, v9, v0
	v_lshl_or_b32 v0, v15, 1, v241
	v_lshlrev_b32_e32 v19, 3, v238
	v_cndmask_b32_e32 v9, v252, v9, vcc
	v_lshlrev_b32_e32 v9, 2, v9
	v_and_b32_e32 v246, 56, v19
	v_and_b32_e32 v16, 24, v19
	v_lshlrev_b32_e32 v13, 10, v18
	v_lshlrev_b32_e32 v245, 9, v18
	v_lshlrev_b32_e32 v18, 1, v246
	v_mov_b32_e32 v19, v189
	v_lshlrev_b32_e32 v10, 1, v238
	v_and_b32_e32 v10, 32, v10
	v_lshlrev_b32_e32 v14, 4, v239
	v_add_u32_e32 v21, 0, v10
	v_bfe_u32 v240, v238, 2, 4
	s_mov_b32 s1, 0
	v_add3_u32 v242, 0, v13, v14
	v_add3_u32 v244, v21, v16, v20
	v_mov_b32_e32 v201, v189
	v_mov_b32_e32 v205, v189
	v_mov_b32_e32 v209, v189
	v_mov_b32_e32 v213, v189
	v_lshlrev_b32_e32 v218, 1, v16
	s_movk_i32 s42, 0x400
	s_movk_i32 s43, 0x801
	s_movk_i32 s44, 0x201
	s_mov_b32 s45, 0x2aaaaaab
	s_movk_i32 s52, 0x7fc0
	s_movk_i32 s54, 0x510
	s_movk_i32 s55, 0xffd0
	s_waitcnt vmcnt(0)
	v_and_b32_e32 v11, 0x7fffffff, v2
	v_and_b32_e32 v12, 0x7fffffff, v3
	ds_bpermute_b32 v11, v4, v11
	ds_bpermute_b32 v4, v4, v12
	v_max_f32_e64 v2, |v2|, |v2|
	v_max_f32_e64 v3, |v3|, |v3|
	s_waitcnt lgkmcnt(1)
	v_max_f32_e32 v11, v11, v11
	s_waitcnt lgkmcnt(0)
	v_max_f32_e32 v4, v4, v4
	v_max_f32_e32 v2, v2, v11
	v_max_f32_e32 v3, v3, v4
	ds_bpermute_b32 v4, v5, v2
	ds_bpermute_b32 v5, v5, v3
	s_waitcnt lgkmcnt(1)
	v_max_f32_e32 v4, v4, v4
	s_waitcnt lgkmcnt(0)
	v_max_f32_e32 v5, v5, v5
	v_max_f32_e32 v4, v2, v4
	v_max_f32_e32 v5, v3, v5
	ds_bpermute_b32 v11, v6, v4
	ds_bpermute_b32 v6, v6, v5
	v_lshl_add_u64 v[2:3], s[12:13], 0, v[188:189]
	s_mov_b64 s[12:13], 0xd001e00
	v_lshl_add_u64 v[190:191], v[2:3], 0, s[12:13]
	s_waitcnt lgkmcnt(1)
	v_max_f32_e32 v2, v11, v11
	s_waitcnt lgkmcnt(0)
	v_max_f32_e32 v3, v6, v6
	v_max_f32_e32 v2, v4, v2
	v_max_f32_e32 v3, v5, v3
	ds_bpermute_b32 v4, v7, v2
	ds_bpermute_b32 v5, v7, v3
	s_add_u32 s12, s14, s4
	s_addc_u32 s13, s15, s5
	v_lshl_add_u64 v[0:1], s[12:13], 0, v[0:1]
	s_waitcnt lgkmcnt(1)
	v_max_f32_e32 v4, v4, v4
	s_waitcnt lgkmcnt(0)
	v_max_f32_e32 v5, v5, v5
	v_max_f32_e32 v2, v2, v4
	v_max_f32_e32 v3, v3, v5
	ds_bpermute_b32 v4, v8, v2
	ds_bpermute_b32 v5, v8, v3
	s_mov_b64 s[4:5], 0xd001a00
	v_lshl_add_u64 v[192:193], v[0:1], 0, s[4:5]
	s_cmp_lg_u32 0, -1
	s_waitcnt lgkmcnt(1)
	v_max_f32_e32 v0, v4, v4
	s_waitcnt lgkmcnt(0)
	v_max_f32_e32 v1, v5, v5
	v_max_f32_e32 v0, v2, v0
	v_max_f32_e32 v1, v3, v1
	ds_bpermute_b32 v2, v9, v0
	ds_bpermute_b32 v3, v9, v1
	s_cselect_b32 s14, 0, 0
	v_lshl_add_u64 v[18:19], s[12:13], 0, v[18:19]
	s_mov_b64 s[12:13], 0xd002000
	s_addk_i32 s14, 0x6000
	s_waitcnt lgkmcnt(1)
	v_max_f32_e32 v2, v2, v2
	v_lshl_add_u64 v[194:195], v[18:19], 0, s[12:13]
	s_mov_b64 s[12:13], 0x1ce00800
	s_waitcnt lgkmcnt(0)
	v_max_f32_e32 v3, v3, v3
	v_max_f32_e32 v0, v0, v2
	v_lshl_add_u64 v[196:197], v[18:19], 0, s[12:13]
	s_add_u32 s12, s8, s10
	v_add_u32_e32 v4, s14, v10
	v_max_f32_e32 v1, v1, v3
	v_mul_f32_e32 v0, 0x41000000, v0
	s_addc_u32 s13, s9, s11
	v_readlane_b32 s14, v255, 22
	v_mul_f32_e32 v0, v1, v0
	s_add_u32 s12, s14, s12
	v_readlane_b32 s14, v255, 23
	v_readfirstlane_b32 s4, v0
	v_mov_b32_e32 v0, 0x3fb8aa3b
	s_addc_u32 s13, s14, s13
	v_mul_f32_e32 v0, s4, v0
	v_cmp_gt_u32_e64 s[4:5], 32, v17
	v_bfe_u32 v17, v238, 3, 3
	v_lshl_add_u64 v[214:215], s[12:13], 0, v[188:189]
	v_readlane_b32 s12, v255, 24
	v_or_b32_e32 v18, 8, v17
	s_add_u32 s10, s12, s10
	v_readlane_b32 s12, v255, 25
	v_lshlrev_b32_e32 v247, 7, v17
	v_mul_hi_u32_u24_e32 v199, 0x3480, v17
	v_mul_u32_u24_e32 v198, 0x3480, v17
	v_lshlrev_b32_e32 v200, 12, v17
	v_lshlrev_b32_e32 v248, 7, v18
	v_mul_hi_u32_u24_e32 v203, 0x3480, v18
	v_mul_u32_u24_e32 v202, 0x3480, v18
	v_lshlrev_b32_e32 v204, 12, v18
	v_or_b32_e32 v18, 16, v17
	v_or_b32_e32 v17, 24, v17
	s_addc_u32 s11, s12, s11
	v_lshlrev_b32_e32 v250, 7, v17
	v_mul_hi_u32_u24_e32 v211, 0x3480, v17
	v_mul_u32_u24_e32 v210, 0x3480, v17
	v_lshlrev_b32_e32 v212, 12, v17
	v_and_b32_e32 v17, 3, v238
	s_add_u32 s8, s10, s8
	v_mul_f32_e32 v0, 0xbf828f5c, v0
	v_lshlrev_b32_e32 v188, 4, v17
	s_addc_u32 s9, s11, s9
	v_add3_u32 v243, v4, v16, v20
	v_mov_b32_e32 v1, v0
	v_mov_b32_e32 v2, v0
	v_mov_b32_e32 v3, v0
	v_mov_b32_e32 v4, v0
	v_mov_b32_e32 v5, v0
	v_mov_b32_e32 v6, v0
	v_mov_b32_e32 v7, v0
	v_mov_b32_e32 v8, v0
	v_mov_b32_e32 v9, v0
	v_mov_b32_e32 v10, v0
	v_mov_b32_e32 v11, v0
	v_mov_b32_e32 v12, v0
	v_mov_b32_e32 v13, v0
	v_mov_b32_e32 v14, v0
	v_mov_b32_e32 v15, v0
	v_lshlrev_b32_e32 v249, 7, v18
	v_mul_hi_u32_u24_e32 v207, 0x3480, v18
	v_mul_u32_u24_e32 v206, 0x3480, v18
	v_lshlrev_b32_e32 v208, 12, v18
	v_lshl_add_u64 v[216:217], s[8:9], 0, v[188:189]
	s_mov_b64 s[10:11], -1
	s_branch .LBB0_387
	s_nop 0
	s_nop 0
; __device__ __forceinline__ int crow(int r, int hi) { return (r & 3) + 8 * (r >> 2) + 4 * hi; }
; template <int THRL> __device__ __forceinline__ void attn_unit(const int tid, const float mfix, int q0, int NT, const bf16* Qh, const bf16* __restrict__ Kh, const bf16* __restrict__ Vh, const bf16* Zh, bf16* Oh, const long PQ, const long PO, char* shm) {
;     ...
;   { auto rr = __builtin_amdgcn_permlane32_swap(__float_as_uint(l_reg), __float_as_uint(l_reg), false, false); l_reg = __uint_as_float(rr[0]) + __uint_as_float(rr[1]); }
;   if (hi == 0) wsf[32 + r32] = l_reg; asm volatile("s_waitcnt lgkmcnt(0)" ::: "memory");
;   float rli[16];
;   #pragma unroll
;   for (int r = 0; r < 16; ++r) rli[r] = __builtin_amdgcn_rcpf(wsf[32 + crow(r, hi)]);
;   bf16* Ow = Oh + (long)(q0 + wid * QBLK) * PO;
;   const bf16* Zw = Zh + (long)(q0 + wid * QBLK) * PQ;
;   { bf16* stg = (bf16*)(shm + LDS_OST) + wid * 2048;
;     #pragma unroll
;     for (int r = 0; r < 16; ++r) { const int orow = crow(r, hi);
;       #pragma unroll
;       for (int d0 = 0; d0 < 2; ++d0) stg[orow * 64 + d0 * 32 + r32] = __float2bfloat16(o[d0][r] * rli[r]); }
;     asm volatile("s_waitcnt lgkmcnt(0)" ::: "memory");
;     #pragma unroll
;     for (int i = 0; i < 4; ++i) { const int row = i * 8 + (lane >> 3), ch = lane & 7; const u32x4 v = *(const u32x4*)(stg + row * 64 + ch * 8);
;       const u32x4 z = *(const u32x4*)(Zw + (long)row * PQ + ch * 8); u32x4 w;
.LBB0_386:
	s_or_b64 exec, exec, s[14:15]
	s_waitcnt lgkmcnt(0)
	v_add_u32_e32 v56, s16, v241
	ds_read_b128 v[48:51], v56 offset:49280
	ds_read_b128 v[52:55], v56 offset:49312
	s_lshl_b32 s1, s1, 12
	s_add_i32 s1, s1, 0
	s_lshl_b64 s[10:11], s[10:11], 12
	s_waitcnt lgkmcnt(1)
	v_rcp_f32_e32 v57, v48
	v_rcp_f32_e32 v58, v49
	v_rcp_f32_e32 v59, v50
	v_rcp_f32_e32 v60, v51
	s_waitcnt lgkmcnt(0)
	v_rcp_f32_e32 v61, v52
	ds_read_b128 v[48:51], v56 offset:49344
	v_rcp_f32_e32 v62, v53
	v_rcp_f32_e32 v63, v54
	v_rcp_f32_e32 v64, v55
	ds_read_b128 v[52:55], v56 offset:49376
	v_lshlrev_b32_e32 v56, 1, v239
	v_mul_f32_e32 v16, v16, v57
	v_add3_u32 v56, s1, v245, v56
	v_cvt_pk_bf16_f32 v16, v16, s0
	ds_write_b16 v56, v16 offset:51200
	v_mul_f32_e32 v16, v32, v57
	v_cvt_pk_bf16_f32 v16, v16, s0
	ds_write_b16 v56, v16 offset:51264
	v_mul_f32_e32 v16, v17, v58
	v_cvt_pk_bf16_f32 v16, v16, s0
	ds_write_b16 v56, v16 offset:51328
	v_mul_f32_e32 v16, v33, v58
	v_cvt_pk_bf16_f32 v16, v16, s0
	ds_write_b16 v56, v16 offset:51392
	v_mul_f32_e32 v16, v18, v59
	v_cvt_pk_bf16_f32 v16, v16, s0
	ds_write_b16 v56, v16 offset:51456
	v_mul_f32_e32 v16, v34, v59
	v_cvt_pk_bf16_f32 v16, v16, s0
	ds_write_b16 v56, v16 offset:51520
	v_mul_f32_e32 v16, v19, v60
	v_cvt_pk_bf16_f32 v16, v16, s0
	ds_write_b16 v56, v16 offset:51584
	v_mul_f32_e32 v16, v35, v60
	v_cvt_pk_bf16_f32 v16, v16, s0
	ds_write_b16 v56, v16 offset:51648
	v_mul_f32_e32 v16, v20, v61
	v_cvt_pk_bf16_f32 v16, v16, s0
	ds_write_b16 v56, v16 offset:52224
	v_mul_f32_e32 v16, v36, v61
	v_cvt_pk_bf16_f32 v16, v16, s0
	ds_write_b16 v56, v16 offset:52288
	v_mul_f32_e32 v16, v21, v62
	v_cvt_pk_bf16_f32 v16, v16, s0
	ds_write_b16 v56, v16 offset:52352
	v_mul_f32_e32 v16, v37, v62
	v_cvt_pk_bf16_f32 v16, v16, s0
	ds_write_b16 v56, v16 offset:52416
	v_mul_f32_e32 v16, v22, v63
	v_cvt_pk_bf16_f32 v16, v16, s0
	ds_write_b16 v56, v16 offset:52480
	v_mul_f32_e32 v16, v38, v63
	v_cvt_pk_bf16_f32 v16, v16, s0
	s_waitcnt lgkmcnt(14)
	v_rcp_f32_e32 v48, v48
	ds_write_b16 v56, v16 offset:52544
	v_mul_f32_e32 v16, v23, v64
	v_cvt_pk_bf16_f32 v16, v16, s0
	ds_write_b16 v56, v16 offset:52608
	v_mul_f32_e32 v16, v39, v64
	v_cvt_pk_bf16_f32 v16, v16, s0
	v_rcp_f32_e32 v49, v49
	ds_write_b16 v56, v16 offset:52672
	v_mul_f32_e32 v16, v24, v48
	v_cvt_pk_bf16_f32 v16, v16, s0
	ds_write_b16 v56, v16 offset:53248
	v_mul_f32_e32 v16, v40, v48
	v_cvt_pk_bf16_f32 v16, v16, s0
	v_rcp_f32_e32 v50, v50
	ds_write_b16 v56, v16 offset:53312
	v_mul_f32_e32 v16, v25, v49
	v_cvt_pk_bf16_f32 v16, v16, s0
	ds_write_b16 v56, v16 offset:53376
	v_mul_f32_e32 v16, v41, v49
	v_cvt_pk_bf16_f32 v16, v16, s0
	v_rcp_f32_e32 v51, v51
	ds_write_b16 v56, v16 offset:53440
	v_mul_f32_e32 v16, v26, v50
	v_cvt_pk_bf16_f32 v16, v16, s0
	ds_write_b16 v56, v16 offset:53504
	v_mul_f32_e32 v16, v42, v50
	v_cvt_pk_bf16_f32 v16, v16, s0
	s_waitcnt lgkmcnt(14)
	v_rcp_f32_e32 v52, v52
	ds_write_b16 v56, v16 offset:53568
	v_mul_f32_e32 v16, v27, v51
	v_cvt_pk_bf16_f32 v16, v16, s0
	ds_write_b16 v56, v16 offset:53632
	v_mul_f32_e32 v16, v43, v51
	v_cvt_pk_bf16_f32 v16, v16, s0
	v_rcp_f32_e32 v53, v53
	ds_write_b16 v56, v16 offset:53696
	v_mul_f32_e32 v16, v28, v52
	v_cvt_pk_bf16_f32 v16, v16, s0
	ds_write_b16 v56, v16 offset:54272
	v_mul_f32_e32 v16, v44, v52
	v_cvt_pk_bf16_f32 v16, v16, s0
	v_rcp_f32_e32 v54, v54
	ds_write_b16 v56, v16 offset:54336
	v_mul_f32_e32 v16, v29, v53
	v_cvt_pk_bf16_f32 v16, v16, s0
	ds_write_b16 v56, v16 offset:54400
	v_mul_f32_e32 v16, v45, v53
	v_cvt_pk_bf16_f32 v16, v16, s0
	v_rcp_f32_e32 v55, v55
	ds_write_b16 v56, v16 offset:54464
	v_mul_f32_e32 v16, v30, v54
	v_cvt_pk_bf16_f32 v16, v16, s0
	ds_write_b16 v56, v16 offset:54528
	v_mul_f32_e32 v16, v46, v54
	v_cvt_pk_bf16_f32 v16, v16, s0
	ds_write_b16 v56, v16 offset:54592
	v_mul_f32_e32 v16, v31, v55
	v_cvt_pk_bf16_f32 v16, v16, s0
	ds_write_b16 v56, v16 offset:54656
	v_mul_f32_e32 v16, v47, v55
	v_cvt_pk_bf16_f32 v16, v16, s0
	ds_write_b16 v56, v16 offset:54720
	v_lshl_add_u64 v[18:19], s[12:13], 1, v[194:195]
	s_waitcnt lgkmcnt(0)
	v_lshl_add_u64 v[16:17], v[18:19], 0, v[198:199]
	global_load_dwordx4 v[20:23], v[16:17], off
	v_lshl_add_u64 v[112:113], v[18:19], 0, v[202:203]
	global_load_dwordx4 v[100:103], v[112:113], off
	v_lshl_add_u64 v[112:113], v[18:19], 0, v[206:207]
	global_load_dwordx4 v[104:107], v[112:113], off
	v_lshl_add_u64 v[112:113], v[18:19], 0, v[210:211]
	global_load_dwordx4 v[108:111], v[112:113], off
	v_lshl_add_u32 v38, v246, 1, s1
	v_add_u32_e32 v16, v38, v247
	ds_read_b128 v[24:27], v16 offset:51200
	s_mov_b32 s1, 1
	s_and_b64 vcc, exec, s[8:9]
	s_waitcnt lgkmcnt(0)
	v_lshlrev_b32_e32 v32, 16, v24
	v_and_b32_e32 v33, 0xffff0000, v24
	s_waitcnt vmcnt(0)
; __device__ __forceinline__ unsigned cvt_pk_bf16(float lo, float hi) { f32x2_c v = {lo, hi}; bf16x2_c b = __builtin_convertvector(v, bf16x2_c); return __builtin_bit_cast(unsigned, b); }
; __device__ __forceinline__ float silu_f(float z) { return z * __builtin_amdgcn_rcpf(1.f + __expf(-z)); }
; template <int THRL> __device__ __forceinline__ void attn_unit(const int tid, const float mfix, int q0, int NT, const bf16* Qh, const bf16* __restrict__ Kh, const bf16* __restrict__ Vh, const bf16* Zh, bf16* Oh, const long PQ, const long PO, char* shm) {
;     ...
;     for (int i = 0; i < 4; ++i) { const int row = i * 8 + (lane >> 3), ch = lane & 7; const u32x4 v = *(const u32x4*)(stg + row * 64 + ch * 8);
;       const u32x4 z = *(const u32x4*)(Zw + (long)row * PQ + ch * 8); u32x4 w;
;       #pragma unroll
;       for (int e = 0; e < 4; ++e) w[e] = cvt_pk_bf16(bf_lo(v[e]) * silu_f(bf_lo(z[e])), bf_hi(v[e]) * silu_f(bf_hi(z[e])));
;       *(u32x4*)(Ow + (long)row * PO + ch * 8) = w; } }
	v_lshlrev_b32_e32 v28, 16, v20
	v_and_b32_e32 v29, 0xffff0000, v20
	v_mul_f32_e32 v17, 0xbfb8aa3b, v28
	v_exp_f32_e32 v17, v17
	v_mul_f32_e32 v20, 0xbfb8aa3b, v29
	v_exp_f32_e32 v20, v20
	v_add_f32_e32 v16, 1.0, v17
	v_rcp_f32_e32 v30, v16
	v_add_f32_e32 v16, 1.0, v20
	v_rcp_f32_e32 v31, v16
	v_lshl_add_u64 v[16:17], v[196:197], 0, s[10:11]
	s_mov_b64 s[10:11], 0
	v_pk_mul_f32 v[28:29], v[30:31], v[28:29]
	v_lshlrev_b32_e32 v30, 16, v21
	v_and_b32_e32 v31, 0xffff0000, v21
	v_mul_f32_e32 v20, 0xbfb8aa3b, v30
	v_exp_f32_e32 v24, v20
	v_mul_f32_e32 v20, 0xbfb8aa3b, v31
	v_exp_f32_e32 v34, v20
	v_pk_mul_f32 v[20:21], v[28:29], v[32:33]
	v_add_f32_e32 v24, 1.0, v24
	v_rcp_f32_e32 v28, v24
	v_add_f32_e32 v24, 1.0, v34
	v_rcp_f32_e32 v29, v24
	v_cvt_pk_bf16_f32 v20, v20, v21
	v_lshlrev_b32_e32 v24, 16, v25
	v_and_b32_e32 v25, 0xffff0000, v25
	v_pk_mul_f32 v[28:29], v[28:29], v[30:31]
	v_lshlrev_b32_e32 v30, 16, v22
	v_and_b32_e32 v31, 0xffff0000, v22
	v_mul_f32_e32 v21, 0xbfb8aa3b, v30
	v_exp_f32_e32 v21, v21
	v_mul_f32_e32 v22, 0xbfb8aa3b, v31
	v_exp_f32_e32 v22, v22
	v_pk_mul_f32 v[24:25], v[28:29], v[24:25]
	v_add_f32_e32 v21, 1.0, v21
	v_rcp_f32_e32 v28, v21
	v_add_f32_e32 v21, 1.0, v22
	v_rcp_f32_e32 v29, v21
	v_cvt_pk_bf16_f32 v21, v24, v25
	v_lshlrev_b32_e32 v24, 16, v26
	v_and_b32_e32 v25, 0xffff0000, v26
	v_pk_mul_f32 v[28:29], v[28:29], v[30:31]
	v_lshlrev_b32_e32 v30, 16, v23
	v_and_b32_e32 v31, 0xffff0000, v23
	v_mul_f32_e32 v22, 0xbfb8aa3b, v30
	v_exp_f32_e32 v26, v22
	v_mul_f32_e32 v22, 0xbfb8aa3b, v31
	v_exp_f32_e32 v32, v22
	v_pk_mul_f32 v[22:23], v[28:29], v[24:25]
	v_add_f32_e32 v24, 1.0, v26
	v_rcp_f32_e32 v24, v24
	v_add_f32_e32 v25, 1.0, v32
	v_rcp_f32_e32 v25, v25
	v_lshlrev_b32_e32 v26, 16, v27
	v_and_b32_e32 v27, 0xffff0000, v27
	v_cvt_pk_bf16_f32 v22, v22, v23
	v_pk_mul_f32 v[24:25], v[24:25], v[30:31]
	s_nop 0
	v_pk_mul_f32 v[24:25], v[24:25], v[26:27]
	s_nop 0
	v_cvt_pk_bf16_f32 v23, v24, v25
	v_lshl_add_u64 v[24:25], v[16:17], 0, v[200:201]
	global_store_dwordx4 v[24:25], v[20:23], off
	v_add_u32_e32 v24, v38, v248
	s_nop 0
	v_mov_b64_e32 v[20:21], v[100:101]
	v_mov_b64_e32 v[22:23], v[102:103]
	v_lshlrev_b32_e32 v28, 16, v20
	v_and_b32_e32 v29, 0xffff0000, v20
	v_mul_f32_e32 v20, 0xbfb8aa3b, v28
	v_exp_f32_e32 v20, v20
	v_mul_f32_e32 v25, 0xbfb8aa3b, v29
	v_exp_f32_e32 v31, v25
	ds_read_b128 v[24:27], v24 offset:51200
	v_add_f32_e32 v20, 1.0, v20
	v_rcp_f32_e32 v30, v20
	v_add_f32_e32 v20, 1.0, v31
	v_rcp_f32_e32 v31, v20
	s_waitcnt lgkmcnt(0)
	v_lshlrev_b32_e32 v32, 16, v24
	v_and_b32_e32 v33, 0xffff0000, v24
	v_pk_mul_f32 v[28:29], v[30:31], v[28:29]
	v_lshlrev_b32_e32 v30, 16, v21
	v_and_b32_e32 v31, 0xffff0000, v21
	v_mul_f32_e32 v20, 0xbfb8aa3b, v30
	v_exp_f32_e32 v24, v20
	v_mul_f32_e32 v20, 0xbfb8aa3b, v31
	v_exp_f32_e32 v34, v20
	v_pk_mul_f32 v[20:21], v[28:29], v[32:33]
	v_add_f32_e32 v24, 1.0, v24
	v_rcp_f32_e32 v28, v24
	v_add_f32_e32 v24, 1.0, v34
	v_rcp_f32_e32 v29, v24
	v_cvt_pk_bf16_f32 v20, v20, v21
	v_lshlrev_b32_e32 v24, 16, v25
	v_and_b32_e32 v25, 0xffff0000, v25
	v_pk_mul_f32 v[28:29], v[28:29], v[30:31]
	v_lshlrev_b32_e32 v30, 16, v22
	v_and_b32_e32 v31, 0xffff0000, v22
	v_mul_f32_e32 v21, 0xbfb8aa3b, v30
	v_exp_f32_e32 v21, v21
	v_mul_f32_e32 v22, 0xbfb8aa3b, v31
	v_exp_f32_e32 v22, v22
	v_pk_mul_f32 v[24:25], v[28:29], v[24:25]
	v_add_f32_e32 v21, 1.0, v21
	v_rcp_f32_e32 v28, v21
	v_add_f32_e32 v21, 1.0, v22
	v_rcp_f32_e32 v29, v21
	v_cvt_pk_bf16_f32 v21, v24, v25
	v_lshlrev_b32_e32 v24, 16, v26
	v_and_b32_e32 v25, 0xffff0000, v26
	v_pk_mul_f32 v[28:29], v[28:29], v[30:31]
	v_lshlrev_b32_e32 v30, 16, v23
	v_and_b32_e32 v31, 0xffff0000, v23
	v_mul_f32_e32 v22, 0xbfb8aa3b, v30
	v_exp_f32_e32 v26, v22
	v_mul_f32_e32 v22, 0xbfb8aa3b, v31
	v_exp_f32_e32 v32, v22
	v_pk_mul_f32 v[22:23], v[28:29], v[24:25]
	v_add_f32_e32 v24, 1.0, v26
	v_rcp_f32_e32 v24, v24
	v_add_f32_e32 v25, 1.0, v32
	v_rcp_f32_e32 v25, v25
	v_lshlrev_b32_e32 v26, 16, v27
	v_and_b32_e32 v27, 0xffff0000, v27
	v_cvt_pk_bf16_f32 v22, v22, v23
	v_pk_mul_f32 v[24:25], v[24:25], v[30:31]
	s_nop 0
	v_pk_mul_f32 v[24:25], v[24:25], v[26:27]
	s_nop 0
	v_cvt_pk_bf16_f32 v23, v24, v25
	v_lshl_add_u64 v[24:25], v[16:17], 0, v[204:205]
	global_store_dwordx4 v[24:25], v[20:23], off
	v_add_u32_e32 v24, v38, v249
	ds_read_b128 v[24:27], v24 offset:51200
	v_mov_b64_e32 v[20:21], v[104:105]
	v_mov_b64_e32 v[22:23], v[106:107]
	v_lshl_add_u64 v[18:19], v[18:19], 0, v[210:211]
	s_waitcnt lgkmcnt(0)
; __device__ __forceinline__ unsigned cvt_pk_bf16(float lo, float hi) { f32x2_c v = {lo, hi}; bf16x2_c b = __builtin_convertvector(v, bf16x2_c); return __builtin_bit_cast(unsigned, b); }
; __device__ __forceinline__ float silu_f(float z) { return z * __builtin_amdgcn_rcpf(1.f + __expf(-z)); }
; template <int THRL> __device__ __forceinline__ void attn_unit(const int tid, const float mfix, int q0, int NT, const bf16* Qh, const bf16* __restrict__ Kh, const bf16* __restrict__ Vh, const bf16* Zh, bf16* Oh, const long PQ, const long PO, char* shm) {
;     ...
;     for (int i = 0; i < 4; ++i) { const int row = i * 8 + (lane >> 3), ch = lane & 7; const u32x4 v = *(const u32x4*)(stg + row * 64 + ch * 8);
;       const u32x4 z = *(const u32x4*)(Zw + (long)row * PQ + ch * 8); u32x4 w;
;       #pragma unroll
;       for (int e = 0; e < 4; ++e) w[e] = cvt_pk_bf16(bf_lo(v[e]) * silu_f(bf_lo(z[e])), bf_hi(v[e]) * silu_f(bf_hi(z[e])));
;       *(u32x4*)(Ow + (long)row * PO + ch * 8) = w; } }
;   asm volatile("s_waitcnt lgkmcnt(0)\n\ts_barrier" ::: "memory");
	v_lshlrev_b32_e32 v28, 16, v24
	v_and_b32_e32 v29, 0xffff0000, v24
	v_lshlrev_b32_e32 v24, 16, v25
	v_and_b32_e32 v25, 0xffff0000, v25
	v_lshlrev_b32_e32 v30, 16, v20
	v_and_b32_e32 v31, 0xffff0000, v20
	v_lshlrev_b32_e32 v20, 16, v21
	v_and_b32_e32 v21, 0xffff0000, v21
	v_lshlrev_b32_e32 v32, 16, v22
	v_and_b32_e32 v33, 0xffff0000, v22
	v_mul_f32_e32 v22, 0xbfb8aa3b, v30
	v_mul_f32_e32 v34, 0xbfb8aa3b, v31
	v_mul_f32_e32 v35, 0xbfb8aa3b, v20
	v_mul_f32_e32 v36, 0xbfb8aa3b, v21
	v_exp_f32_e32 v22, v22
	v_exp_f32_e32 v34, v34
	v_exp_f32_e32 v35, v35
	v_exp_f32_e32 v36, v36
	v_add_f32_e32 v22, 1.0, v22
	v_add_f32_e32 v37, 1.0, v34
	v_add_f32_e32 v41, 1.0, v35
	v_add_f32_e32 v42, 1.0, v36
	v_mul_f32_e32 v39, 0xbfb8aa3b, v32
	v_rcp_f32_e32 v34, v22
	v_rcp_f32_e32 v35, v37
	v_rcp_f32_e32 v36, v41
	v_rcp_f32_e32 v37, v42
	v_mul_f32_e32 v40, 0xbfb8aa3b, v33
	v_exp_f32_e32 v22, v39
	v_exp_f32_e32 v39, v40
	v_pk_mul_f32 v[30:31], v[34:35], v[30:31]
	v_pk_mul_f32 v[20:21], v[36:37], v[20:21]
	v_pk_mul_f32 v[28:29], v[30:31], v[28:29]
	v_pk_mul_f32 v[24:25], v[20:21], v[24:25]
	v_add_f32_e32 v21, 1.0, v22
	v_cvt_pk_bf16_f32 v20, v28, v29
	v_rcp_f32_e32 v28, v21
	v_add_f32_e32 v21, 1.0, v39
	v_rcp_f32_e32 v29, v21
	v_lshlrev_b32_e32 v30, 16, v23
	v_and_b32_e32 v31, 0xffff0000, v23
	v_mul_f32_e32 v22, 0xbfb8aa3b, v30
	v_cvt_pk_bf16_f32 v21, v24, v25
	v_lshlrev_b32_e32 v24, 16, v26
	v_and_b32_e32 v25, 0xffff0000, v26
	v_exp_f32_e32 v26, v22
	v_mul_f32_e32 v22, 0xbfb8aa3b, v31
	v_pk_mul_f32 v[28:29], v[28:29], v[32:33]
	v_exp_f32_e32 v32, v22
	v_pk_mul_f32 v[22:23], v[28:29], v[24:25]
	v_add_f32_e32 v24, 1.0, v26
	v_rcp_f32_e32 v24, v24
	v_add_f32_e32 v25, 1.0, v32
	v_rcp_f32_e32 v25, v25
	v_lshlrev_b32_e32 v26, 16, v27
	v_and_b32_e32 v27, 0xffff0000, v27
	v_cvt_pk_bf16_f32 v22, v22, v23
	v_pk_mul_f32 v[24:25], v[24:25], v[30:31]
	s_nop 0
	v_pk_mul_f32 v[24:25], v[24:25], v[26:27]
	v_lshl_add_u64 v[26:27], v[16:17], 0, v[212:213]
	v_cvt_pk_bf16_f32 v23, v24, v25
	v_lshl_add_u64 v[24:25], v[16:17], 0, v[208:209]
	global_store_dwordx4 v[24:25], v[20:23], off
	s_nop 1
	v_mov_b64_e32 v[18:19], v[108:109]
	v_mov_b64_e32 v[20:21], v[110:111]
	v_lshlrev_b32_e32 v30, 16, v18
	v_and_b32_e32 v31, 0xffff0000, v18
	v_lshlrev_b32_e32 v18, 16, v19
	v_and_b32_e32 v19, 0xffff0000, v19
	v_lshlrev_b32_e32 v32, 16, v20
	v_and_b32_e32 v33, 0xffff0000, v20
	v_lshlrev_b32_e32 v20, 16, v21
	v_and_b32_e32 v21, 0xffff0000, v21
	v_add_u32_e32 v22, v38, v250
	v_mul_f32_e32 v34, 0xbfb8aa3b, v30
	v_mul_f32_e32 v35, 0xbfb8aa3b, v31
	v_mul_f32_e32 v36, 0xbfb8aa3b, v18
	v_mul_f32_e32 v37, 0xbfb8aa3b, v19
	v_mul_f32_e32 v38, 0xbfb8aa3b, v32
	v_mul_f32_e32 v39, 0xbfb8aa3b, v33
	v_mul_f32_e32 v40, 0xbfb8aa3b, v20
	v_mul_f32_e32 v41, 0xbfb8aa3b, v21
	v_exp_f32_e32 v34, v34
	v_exp_f32_e32 v35, v35
	v_exp_f32_e32 v36, v36
	v_exp_f32_e32 v37, v37
	v_exp_f32_e32 v38, v38
	v_exp_f32_e32 v39, v39
	v_exp_f32_e32 v40, v40
	v_exp_f32_e32 v41, v41
	ds_read_b128 v[22:25], v22 offset:51200
	v_add_f32_e32 v34, 1.0, v34
	v_add_f32_e32 v35, 1.0, v35
	v_add_f32_e32 v36, 1.0, v36
	v_add_f32_e32 v37, 1.0, v37
	v_add_f32_e32 v38, 1.0, v38
	v_add_f32_e32 v39, 1.0, v39
	v_add_f32_e32 v40, 1.0, v40
	v_add_f32_e32 v41, 1.0, v41
	v_rcp_f32_e32 v34, v34
	v_rcp_f32_e32 v35, v35
	v_rcp_f32_e32 v36, v36
	v_rcp_f32_e32 v37, v37
	v_rcp_f32_e32 v38, v38
	v_rcp_f32_e32 v39, v39
	v_rcp_f32_e32 v40, v40
	v_rcp_f32_e32 v41, v41
	s_waitcnt lgkmcnt(0)
	v_lshlrev_b32_e32 v16, 16, v22
	v_and_b32_e32 v17, 0xffff0000, v22
	v_lshlrev_b32_e32 v22, 16, v23
	v_and_b32_e32 v23, 0xffff0000, v23
	v_lshlrev_b32_e32 v28, 16, v24
	v_and_b32_e32 v29, 0xffff0000, v24
	v_lshlrev_b32_e32 v24, 16, v25
	v_and_b32_e32 v25, 0xffff0000, v25
	v_pk_mul_f32 v[30:31], v[34:35], v[30:31]
	v_pk_mul_f32 v[18:19], v[36:37], v[18:19]
	v_pk_mul_f32 v[32:33], v[38:39], v[32:33]
	v_pk_mul_f32 v[20:21], v[40:41], v[20:21]
	v_pk_mul_f32 v[16:17], v[30:31], v[16:17]
	v_pk_mul_f32 v[18:19], v[18:19], v[22:23]
	v_pk_mul_f32 v[22:23], v[32:33], v[28:29]
	v_pk_mul_f32 v[20:21], v[20:21], v[24:25]
	v_cvt_pk_bf16_f32 v16, v16, v17
	v_cvt_pk_bf16_f32 v17, v18, v19
	v_cvt_pk_bf16_f32 v18, v22, v23
	v_cvt_pk_bf16_f32 v19, v20, v21
	global_store_dwordx4 v[26:27], v[16:19], off
	s_waitcnt lgkmcnt(0)
	s_barrier
	s_cbranch_vccnz .LBB0_391
